# baseline (speedup 1.0000x reference)
; #define MFMA4(a, b, c) __builtin_amdgcn_mfma_f32_16x16x16bf16_1k(a, b, c, 0, 0, 0)
; __device__ __forceinline__ s4 pack4v(f32x4 v) { return pack4(v[0], v[1], v[2], v[3]); }
; __device__ __forceinline__ void scan_pc(const Params& p, int j, const u16* R, const u16* K, const u16* V, u16* Y, u16* YB) {
;     ...
;       const u16* IMG = shm + (c % 3) * IMG_ELEMS;
;       const u16* MM = shm + 4 * IMG_ELEMS + (c & 1) * MM_ELEMS;
;       s4 vb = *reinterpret_cast<const s4*>(IMG + IMG_VT + (w4 * 16 + fr) * XK_LD + fq * 4);
;       f32x4 z4 = {0.f, 0.f, 0.f, 0.f};
;       const float* PL = reinterpret_cast<const float*>(IMG + IMG_PL);
;       float4 iv = *reinterpret_cast<const float4*>(PL + 192 + fq * 4);
;       f32x4 rhs = z4;
;       f32x4 y = MFMA4(*reinterpret_cast<const s4*>(MM + (3 * 16 + fr) * XK_LD + fq * 4), vb, z4);
;       _Pragma("unroll") for (int kb = 0; kb < 4; ++kb) {
;         rhs = MFMA4(*reinterpret_cast<const s4*>(IMG + (0 * 16 + fr) * XT_LD + kb * 16 + fq * 4), Zb[kb], rhs);
;         y = MFMA4(*reinterpret_cast<const s4*>(IMG + (1 * 16 + fr) * XT_LD + kb * 16 + fq * 4), Zb[kb], y);
;       }
;       rhs[0] *= iv.x; rhs[1] *= iv.y; rhs[2] *= iv.z; rhs[3] *= iv.w;
;       rhs = MFMA4(*reinterpret_cast<const s4*>(MM + (1 * 16 + fr) * XK_LD + fq * 4), vb, rhs);
;       f32x4 u = MFMA4(*reinterpret_cast<const s4*>(MM + (0 * 16 + fr) * XK_LD + fq * 4), pack4v(rhs), z4);
;       y = MFMA4(*reinterpret_cast<const s4*>(MM + (2 * 16 + fr) * XK_LD + fq * 4), pack4v(u), y);
;       s4 ub = pack4(u[0] * iv.x, u[1] * iv.y, u[2] * iv.z, u[3] * iv.w);
;       _Pragma("unroll") for (int kb = 0; kb < 4; ++kb) {
;         Z[kb] = MFMA4(*reinterpret_cast<const s4*>(IMG + IMG_XK + (0 * 64 + kb * 16 + fr) * XK_LD + fq * 4), ub, Z[kb]);
;         Z[kb] = MFMA4(*reinterpret_cast<const s4*>(IMG + IMG_XK + (1 * 64 + kb * 16 + fr) * XK_LD + fq * 4), vb, Z[kb]);
.LBB0_2720:
	s_mul_hi_u32 s26, s28, 0xaaaaaaab
	s_lshr_b32 s26, s26, 1
	s_mul_i32 s26, s26, 3
	s_sub_i32 s75, 1, s26
	v_lshlrev_b32_e32 v179, 1, v97
	s_and_saveexec_b64 s[26:27], s[10:11]
	s_xor_b64 s[26:27], exec, s[26:27]
	s_cbranch_execz .LBB0_2739
	s_mov_b32 s30, 0xaaaaaaab
	v_mul_hi_u32 v50, v90, s30
	v_lshrrev_b32_e32 v50, 1, v50
	v_mad_u64_u32 v[50:51], s[30:31], v50, -3, v[90:91]
	v_mad_u32_u24 v58, v50, s80, 0
	v_add3_u32 v50, v58, v127, v179
	ds_read_b64 v[70:71], v50 offset:14336
	v_lshl_add_u32 v50, v97, 2, v58
	ds_read_b128 v[66:69], v50 offset:17664
	v_add3_u32 v50, v58, v146, v179
	ds_read2_b64 v[60:63], v145 offset0:160 offset1:240
	ds_read2_b64 v[194:197], v50 offset1:4
	v_add_u32_e32 v59, 0x800, v50
	ds_read2_b64 v[202:205], v59 offset0:32 offset1:36
	s_waitcnt lgkmcnt(2)
	v_mfma_f32_16x16x16_bf16 v[92:95], v[62:63], v[70:71], 0
	v_add3_u32 v91, v58, v144, v133
	v_add_u32_e32 v193, 0x2c00, v91
	v_readlane_b32 s76, v247, 14
	s_waitcnt lgkmcnt(1)
	v_mfma_f32_16x16x16_bf16 v[198:201], v[194:195], v[64:65], 0
	v_readlane_b32 s77, v247, 15
	v_readlane_b32 s78, v247, 16
	v_readlane_b32 s79, v247, 17
	s_waitcnt lgkmcnt(0)
	v_mfma_f32_16x16x16_bf16 v[62:65], v[202:203], v[64:65], v[92:95]
	s_mov_b32 s77, s76
	s_mov_b32 s78, s76
	s_mov_b32 s79, s76
	v_mfma_f32_16x16x16_bf16 v[92:95], v[196:197], v[56:57], v[198:201]
	ds_read2_b64 v[194:197], v50 offset0:8 offset1:12
	v_add_u32_e32 v50, 0x2000, v91
	v_writelane_b32 v247, s76, 14
	s_waitcnt lgkmcnt(0)
	v_mfma_f32_16x16x16_bf16 v[92:95], v[194:195], v[52:53], v[92:95]
	ds_read2_b64 v[198:201], v145 offset1:80
	v_writelane_b32 v247, s77, 15
	v_writelane_b32 v247, s78, 16
	v_mfma_f32_16x16x16_bf16 v[92:95], v[196:197], v[48:49], v[92:95]
	ds_read2_b64 v[194:197], v50 offset0:128 offset1:208
	v_writelane_b32 v247, s79, 17
	v_mfma_f32_16x16x16_bf16 v[62:65], v[204:205], v[56:57], v[62:65]
	s_nop 4
	v_mul_f32_e64 v94, v68, v94
	v_mul_f32_e64 v95, v69, v95
	v_mul_f32_e32 v92, v66, v92
	v_mul_f32_e32 v93, v67, v93
	s_waitcnt lgkmcnt(1)
	s_nop 0
	v_mfma_f32_16x16x16_bf16 v[92:95], v[200:201], v[70:71], v[92:95]
	s_nop 7
	v_cvt_pk_bf16_f32 v50, v92, v93
	v_cvt_pk_bf16_f32 v51, v94, v95
	s_nop 1
	v_mfma_f32_16x16x16_bf16 v[92:95], v[198:199], v[50:51], 0
	ds_read2_b64 v[198:201], v59 offset0:40 offset1:44
	s_nop 6
	v_mul_f32_e32 v50, v66, v92
	v_mul_f32_e32 v51, v67, v93
	v_mul_f32_e32 v54, v68, v94
	v_mul_f32_e32 v55, v69, v95
	ds_read2_b64 v[66:69], v193 offset0:64 offset1:144
	v_cvt_pk_bf16_f32 v180, v50, v51
	v_cvt_pk_bf16_f32 v181, v54, v55
	s_waitcnt lgkmcnt(1)
	v_mfma_f32_16x16x16_bf16 v[50:53], v[198:199], v[52:53], v[62:65]
	v_add_u32_e32 v193, v58, v112
	v_add_u32_e32 v54, 0x2800, v91
	v_cvt_pk_bf16_f32 v202, v92, v93
	v_mfma_f32_16x16x16_bf16 v[40:43], v[194:195], v[180:181], v[40:43]
	v_cvt_pk_bf16_f32 v203, v94, v95
	v_mfma_f32_16x16x16_bf16 v[194:197], v[196:197], v[180:181], v[44:47]
	ds_read_b128 v[56:59], v193 offset:16896
	s_nop 1
	ds_read_b128 v[44:47], v193 offset:16960
	s_waitcnt lgkmcnt(2)
	v_mfma_f32_16x16x16_bf16 v[40:43], v[66:67], v[70:71], v[40:43]
	ds_read2_b64 v[64:67], v54 offset0:32 offset1:112
	v_add_u32_e32 v54, 0x3000, v91
	v_add_u32_e32 v91, s74, v166
	v_mfma_f32_16x16x16_bf16 v[92:95], v[200:201], v[48:49], v[50:53]
	ds_read2_b64 v[198:201], v54 offset0:96 offset1:176
	s_nop 1
	ds_read_b128 v[52:55], v193 offset:17024
	ds_read_b128 v[48:51], v193 offset:17088
	v_mfma_f32_16x16x16_bf16 v[92:95], v[60:61], v[202:203], v[92:95]
	s_waitcnt lgkmcnt(3)
	v_mfma_f32_16x16x16_bf16 v[32:35], v[64:65], v[180:181], v[32:35]
	v_mfma_f32_16x16x16_bf16 v[36:39], v[66:67], v[180:181], v[36:39]
	s_andn2_b64 vcc, exec, s[20:21]
	s_cbranch_vccnz .Lyold_done_a
	s_waitcnt vmcnt(0)
	v_lshlrev_b32_e32 v87, 16, v230
	v_lshlrev_b32_e32 v88, 16, v231
	v_lshlrev_b32_e32 v86, 16, v232
	v_lshlrev_b32_e32 v89, 16, v233

; __device__ __forceinline__ float b2f(u16 b) { return __uint_as_float(((unsigned)b) << 16); }
; __device__ __forceinline__ float sigmoidf_(float x) { return __builtin_amdgcn_rcpf(1.f + __builtin_amdgcn_exp2f(-1.4426950408889634f * x)); }
; #define MFMA16(a, b, c) __builtin_amdgcn_mfma_f32_16x16x32_bf16(a, b, c, 0, 0, 0)
; #define MFMA4(a, b, c) __builtin_amdgcn_mfma_f32_16x16x16bf16_1k(a, b, c, 0, 0, 0)
; __device__ __forceinline__ s4 pack4v(f32x4 v) { return pack4(v[0], v[1], v[2], v[3]); }
; __device__ __forceinline__ void scan_pc(const Params& p, int j, const u16* R, const u16* K, const u16* V, u16* Y, u16* YB) {
;     ...
;     auto stage_a = [&](int c, const Raw& q_) {
;       u16* IMG = shm + (c % 3) * IMG_ELEMS;
;       f32x4 cw = {0.f, 0.f, 0.f, 0.f}, ca = {0.f, 0.f, 0.f, 0.f};
;       _Pragma("unroll") for (int ks = 0; ks < 2; ++ks) { cw = MFMA16(q_.rw[ks], LB[ks * 64], cw); ca = MFMA16(q_.ra[ks], LB[(2 + ks) * 64], ca); }
;       float kv[4], kk[4], ic[4], lw[4];
;       _Pragma("unroll") for (int jj = 0; jj < 4; ++jj) {
;         kv[jj] = b2f(q_.rk[jj]);
;         kk[jj] = kv[jj] * kkme;
;         float ss = row_sum(kk[jj] * kk[jj]);
;         reinterpret_cast<float*>(IMG + IMG_PL)[128 + w4 * 16 + fq * 4 + jj] = ss;
;         lw[jj] = -0.8750360036f * sigmoidf_(w0c + cw[jj]);
;         ic[jj] = sigmoidf_(a0c + ca[jj]);
;       }
;       s4 lhi = pack4(lw[0], lw[1], lw[2], lw[3]);
;       s4 llo = pack4(lw[0] - b2f((u16)lhi[0]), lw[1] - b2f((u16)lhi[1]), lw[2] - b2f((u16)lhi[2]), lw[3] - b2f((u16)lhi[3]));
;       f32x4 cum = {0.f, 0.f, 0.f, 0.f};
;       cum = MFMA4(ltri, lhi, cum);
;       cum = MFMA4(ltri, llo, cum);
;       float bt[4], kt[4], ep3 = 0.f;
;       _Pragma("unroll") for (int jj = 0; jj < 4; ++jj) {
;         float ep = __builtin_amdgcn_exp2f(cum[jj]), em = __builtin_amdgcn_exp2f(-cum[jj]), ex = __builtin_amdgcn_exp2f(cum[jj] - lw[jj]);
;         float at = -kk[jj] * ex;
;         float rraw = b2f(q_.rr[jj]);
;         float rt = rraw * ep;
;         float kd = kv[jj] * (1.f + (ic[jj] - 1.f) * kac);
;         bt[jj] = kk[jj] * ic[jj] * em;
;         kt[jj] = kd * em;
;         int t = fq * 4 + jj, kc = w4 * 16 + fr;
;         float bsum = row_sum(rraw * kd * rkc);
;     ...
;         Z[kb][0] *= pl.x; Z[kb][1] *= pl.y; Z[kb][2] *= pl.z; Z[kb][3] *= pl.w;
;         Zb[kb] = pack4v(Z[kb]);
.LBB0_2738:
	s_or_b64 exec, exec, s[62:63]
	v_mul_f32_e32 v40, v40, v56
	v_mul_f32_e32 v41, v41, v57
	v_mul_f32_e32 v42, v42, v58
	v_mul_f32_e32 v43, v43, v59
	v_mul_f32_e32 v44, v60, v44
	v_mul_f32_e32 v45, v61, v45
	v_mul_f32_e32 v46, v62, v46
	v_mul_f32_e32 v47, v63, v47
	s_waitcnt lgkmcnt(1)
	v_mul_f32_e32 v32, v32, v52
	v_mul_f32_e32 v33, v33, v53
	v_mul_f32_e32 v34, v34, v54
	v_mul_f32_e32 v35, v35, v55
	s_waitcnt lgkmcnt(0)
	v_mul_f32_e32 v36, v36, v48
	v_mul_f32_e32 v37, v37, v49
	v_mul_f32_e32 v38, v38, v50
	v_mul_f32_e32 v39, v39, v51
	v_cvt_pk_bf16_f32 v64, v40, v41
	v_cvt_pk_bf16_f32 v65, v42, v43
	v_cvt_pk_bf16_f32 v56, v44, v45
	v_cvt_pk_bf16_f32 v57, v46, v47
	v_cvt_pk_bf16_f32 v52, v32, v33
	v_cvt_pk_bf16_f32 v53, v34, v35
	v_cvt_pk_bf16_f32 v48, v36, v37
	v_cvt_pk_bf16_f32 v49, v38, v39
.LBB0_2739:
	s_or_saveexec_b64 s[26:27], s[26:27]
	s_mul_hi_u32 s30, s3, 0xaaaaaaab
	s_lshr_b32 s30, s30, 1
	s_mul_i32 s30, s30, 3
	s_sub_i32 s76, 2, s30
	v_add_u32_e32 v94, 2, v90
	s_xor_b64 exec, exec, s[26:27]
	s_cbranch_execz .LBB0_2745
	s_waitcnt vmcnt(16)
	v_lshl_or_b32 v161, v207, 16, v206
	v_lshl_or_b32 v159, v209, 16, v208
	v_lshl_or_b32 v160, v211, 16, v210
	v_lshl_or_b32 v158, v213, 16, v212
	v_lshl_or_b32 v82, v215, 16, v214
	v_lshl_or_b32 v83, v217, 16, v216
	v_add_u32_e32 v50, 4, v90
	v_min_i32_e32 v50, s29, v50
	v_mul_lo_u32 v50, v50, s8
	v_add_u32_e32 v51, v50, v154
	v_add_u32_e32 v54, v50, v155
	v_add_u32_e32 v55, v50, v156
	v_add_u32_e32 v50, v50, v157
	global_load_ushort v208, v55, s[58:59]
	global_load_ushort v209, v50, s[58:59]
	global_load_ushort v206, v51, s[58:59]
	global_load_ushort v210, v51, s[54:55]
	global_load_ushort v207, v54, s[58:59]
	global_load_ushort v211, v54, s[54:55]
	global_load_ushort v212, v55, s[54:55]
	global_load_ushort v216, v55, s[4:5]
	global_load_ushort v215, v54, s[4:5]
	global_load_ushort v214, v51, s[4:5]
	global_load_ushort v213, v50, s[54:55]
	global_load_ushort v217, v50, s[4:5]
	v_add_u32_e32 v50, 2, v90
	v_cmp_gt_u32_e32 vcc, s2, v50
	s_and_saveexec_b64 s[30:31], vcc
	s_cbranch_execz .LBB0_2744
	ds_read_b128 v[58:61], v111
	ds_read_b128 v[234:237], v111 offset:2048
	ds_read_b128 v[238:241], v111 offset:1024
	ds_read_b128 v[242:245], v111 offset:3072
	s_mov_b32 s62, 0xbf60025c
	v_add_u32_e32 v50, s76, v90
	s_waitcnt lgkmcnt(3)
	v_mfma_f32_16x16x32_bf16 v[20:23], v[20:23], v[58:61], 0
	s_waitcnt lgkmcnt(2)
	v_mfma_f32_16x16x32_bf16 v[28:31], v[28:31], v[234:237], 0
	s_waitcnt lgkmcnt(1)
	v_mfma_f32_16x16x32_bf16 v[16:19], v[16:19], v[238:241], v[20:23]
	s_waitcnt lgkmcnt(0)
	v_mfma_f32_16x16x32_bf16 v[20:23], v[24:27], v[242:245], v[28:31]
	s_nop 5
	v_add_f32_e32 v16, v152, v16
	v_add_f32_e32 v17, v152, v17
	v_mul_f32_e32 v16, 0xbfb8aa3b, v16
	s_nop 2
	v_add_f32_e32 v20, v153, v20
	v_mul_f32_e32 v20, 0xbfb8aa3b, v20
	v_exp_f32_e32 v20, v20
	v_mul_f32_e32 v17, 0xbfb8aa3b, v17
	v_add_f32_e32 v18, v152, v18
	v_add_f32_e32 v19, v152, v19
	v_add_f32_e32 v20, 1.0, v20
	v_rcp_f32_e32 v26, v20
	v_add_f32_e32 v20, v153, v21
	v_mul_f32_e32 v20, 0xbfb8aa3b, v20
	v_exp_f32_e32 v20, v20
	v_exp_f32_e32 v16, v16
	v_exp_f32_e32 v17, v17
	v_mul_f32_e32 v18, 0xbfb8aa3b, v18
	v_add_f32_e32 v20, 1.0, v20
	v_rcp_f32_e32 v27, v20
	v_add_f32_e32 v20, v153, v22
	v_mul_f32_e32 v20, 0xbfb8aa3b, v20
	v_exp_f32_e32 v20, v20
	v_mul_f32_e32 v19, 0xbfb8aa3b, v19
	v_exp_f32_e32 v18, v18
	v_exp_f32_e32 v19, v19
	v_add_f32_e32 v20, 1.0, v20
	v_rcp_f32_e32 v22, v20
	v_add_f32_e32 v20, v153, v23
	v_add_f32_e32 v16, 1.0, v16
	v_add_f32_e32 v17, 1.0, v17
	v_mul_f32_e32 v20, 0xbfb8aa3b, v20
	v_rcp_f32_e32 v16, v16
	v_rcp_f32_e32 v17, v17
	v_add_f32_e32 v18, 1.0, v18
	v_add_f32_e32 v19, 1.0, v19
	v_exp_f32_e32 v20, v20
	v_rcp_f32_e32 v18, v18
	v_rcp_f32_e32 v19, v19
	v_mul_f32_e64 v28, v16, s62
	v_mul_f32_e64 v29, v17, s62
	v_add_f32_e32 v20, 1.0, v20
	v_rcp_f32_e32 v23, v20
	v_mul_f32_e64 v30, v18, s62
	v_mul_f32_e64 v31, v19, s62
	v_cvt_pk_bf16_f32 v20, v28, v29
	v_mad_u32_u24 v24, v50, s80, 0
	v_cvt_pk_bf16_f32 v21, v30, v31
	v_and_b32_e32 v51, 0xffff0000, v20
	v_lshlrev_b32_e32 v50, 16, v20
	v_fma_f32 v16, v16, s62, -v50
	v_fma_f32 v17, v17, s62, -v51
	v_and_b32_e32 v51, 0xffff0000, v21
	v_lshlrev_b32_e32 v50, 16, v21
	v_fma_f32 v18, v18, s62, -v50
	v_fma_f32 v19, v19, s62, -v51
	v_cvt_pk_bf16_f32 v50, v16, v17
	v_cvt_pk_bf16_f32 v51, v18, v19
	v_mfma_f32_16x16x16_bf16 v[16:19], v[72:73], v[20:21], 0
	v_add_u32_e32 v60, v24, v115
	v_add_u32_e32 v61, v60, v117
	v_add3_u32 v66, v24, v117, v115
	v_mfma_f32_16x16x16_bf16 v[18:21], v[72:73], v[50:51], v[16:19]
	v_add_u32_e32 v25, v24, v113
	v_add_u32_e32 v62, v25, v112
	v_lshl_add_u32 v63, v97, 2, v25
	s_nop 4
	v_sub_f32_e32 v16, v18, v28
	v_exp_f32_e32 v58, v18
	v_exp_f32_e64 v50, -v18
	v_exp_f32_e32 v59, v16
	v_exp_f32_e32 v67, v19
	v_exp_f32_e64 v51, -v19
	v_sub_f32_e32 v16, v19, v29
	v_and_b32_e32 v19, 0xffff0000, v161
	v_lshlrev_b32_e32 v18, 16, v161
	v_mul_f32_e32 v54, v76, v18
	v_mul_f32_e32 v55, v77, v19
	v_exp_f32_e32 v68, v16
	v_mul_f32_e32 v16, v54, v54
	v_mul_f32_e32 v17, v55, v55
	s_nop 1
	v_mov_b32_dpp v16, v16 quad_perm:[1,0,3,2] row_mask:0xf bank_mask:0xf bound_ctrl:1
	v_mov_b32_dpp v17, v17 quad_perm:[1,0,3,2] row_mask:0xf bank_mask:0xf bound_ctrl:1
	v_fma_f32 v16, v54, v54, v16
	v_fma_f32 v17, v55, v55, v17
	s_nop 1
	v_mov_b32_dpp v28, v16 quad_perm:[2,3,0,1] row_mask:0xf bank_mask:0xf bound_ctrl:1
	v_mov_b32_dpp v29, v17 quad_perm:[2,3,0,1] row_mask:0xf bank_mask:0xf bound_ctrl:1
	v_add_f32_e32 v16, v16, v28
	v_add_f32_e32 v17, v17, v29
	s_nop 1
	v_mov_b32_dpp v28, v16 row_half_mirror row_mask:0xf bank_mask:0xf bound_ctrl:1
; __device__ __forceinline__ void scan_pc(const Params& p, int j, const u16* R, const u16* K, const u16* V, u16* Y, u16* YB) {
;     ...
;     auto stage_a = [&](int c, const Raw& q_) {
;       u16* IMG = shm + (c % 3) * IMG_ELEMS;
;       f32x4 cw = {0.f, 0.f, 0.f, 0.f}, ca = {0.f, 0.f, 0.f, 0.f};
;       _Pragma("unroll") for (int ks = 0; ks < 2; ++ks) { cw = MFMA16(q_.rw[ks], LB[ks * 64], cw); ca = MFMA16(q_.ra[ks], LB[(2 + ks) * 64], ca); }
;       float kv[4], kk[4], ic[4], lw[4];
;       _Pragma("unroll") for (int jj = 0; jj < 4; ++jj) {
;         kv[jj] = b2f(q_.rk[jj]);
;         kk[jj] = kv[jj] * kkme;
;         float ss = row_sum(kk[jj] * kk[jj]);
;         reinterpret_cast<float*>(IMG + IMG_PL)[128 + w4 * 16 + fq * 4 + jj] = ss;
;         lw[jj] = -0.8750360036f * sigmoidf_(w0c + cw[jj]);
;         ic[jj] = sigmoidf_(a0c + ca[jj]);
;       }
;       s4 lhi = pack4(lw[0], lw[1], lw[2], lw[3]);
;       s4 llo = pack4(lw[0] - b2f((u16)lhi[0]), lw[1] - b2f((u16)lhi[1]), lw[2] - b2f((u16)lhi[2]), lw[3] - b2f((u16)lhi[3]));
;       f32x4 cum = {0.f, 0.f, 0.f, 0.f};
;       cum = MFMA4(ltri, lhi, cum);
;       cum = MFMA4(ltri, llo, cum);
;       float bt[4], kt[4], ep3 = 0.f;
;       _Pragma("unroll") for (int jj = 0; jj < 4; ++jj) {
;         float ep = __builtin_amdgcn_exp2f(cum[jj]), em = __builtin_amdgcn_exp2f(-cum[jj]), ex = __builtin_amdgcn_exp2f(cum[jj] - lw[jj]);
;         float at = -kk[jj] * ex;
;         float rraw = b2f(q_.rr[jj]);
;         float rt = rraw * ep;
;         float kd = kv[jj] * (1.f + (ic[jj] - 1.f) * kac);
;         bt[jj] = kk[jj] * ic[jj] * em;
;         kt[jj] = kd * em;
;         int t = fq * 4 + jj, kc = w4 * 16 + fr;
;         float bsum = row_sum(rraw * kd * rkc);
;         reinterpret_cast<float*>(IMG + IMG_PL)[64 + w4 * 16 + t] = bsum;
;         IMG[(0 * 16 + t) * XT_LD + kc] = f2b(at);
;         IMG[(1 * 16 + t) * XT_LD + kc] = f2b(rt);
;         IMG[(2 * 16 + t) * XT_LD + kc] = f2b(bt[jj]);
;         IMG[(3 * 16 + t) * XT_LD + kc] = f2b(kt[jj]);
;         if (jj == 3) ep3 = ep;
;       }
;       if (fq == 3) reinterpret_cast<float*>(IMG + IMG_PL)[w4 * 16 + fr] = ep3;
;       *reinterpret_cast<s4*>(IMG + IMG_XK + (0 * 64 + w4 * 16 + fr) * XK_LD + fq * 4) = pack4(bt[0], bt[1], bt[2], bt[3]);
;       *reinterpret_cast<s4*>(IMG + IMG_XK + (1 * 64 + w4 * 16 + fr) * XK_LD + fq * 4) = pack4(kt[0], kt[1], kt[2], kt[3]);
	v_mov_b32_dpp v29, v17 row_half_mirror row_mask:0xf bank_mask:0xf bound_ctrl:1
	v_add_f32_e32 v16, v16, v28
	v_add_f32_e32 v17, v17, v29
	s_nop 1
	v_mov_b32_dpp v28, v16 row_ror:8 row_mask:0xf bank_mask:0xf bound_ctrl:1
	v_mov_b32_dpp v29, v17 row_ror:8 row_mask:0xf bank_mask:0xf bound_ctrl:1
	v_add_f32_e32 v28, v16, v28
	v_add_f32_e32 v29, v17, v29
	v_mul_f32_e64 v16, v59, -v54
	v_cvt_pk_bf16_f32 v16, v16, s0
	ds_write_b16 v61, v16
	v_mul_f32_e32 v16, v54, v26
	v_mul_f32_e32 v17, v55, v27
	v_add_f32_e64 v26, v26, -1.0
	v_add_f32_e64 v27, v27, -1.0
	v_mul_f32_e32 v16, v16, v50
	v_mul_f32_e32 v17, v17, v51
	v_fma_f32 v26, v74, v26, 1.0
	v_fma_f32 v27, v75, v27, 1.0
	v_cvt_pk_bf16_f32 v54, v16, s0
	v_mul_f32_e32 v26, v26, v18
	v_mul_f32_e32 v27, v27, v19
	ds_write_b16 v66, v54 offset:4608
	v_mul_f32_e32 v18, v26, v50
	v_mul_f32_e32 v19, v27, v51
	v_mul_f32_e64 v54, v68, -v55
	v_cvt_pk_bf16_f32 v50, v18, s0
	ds_write_b16 v66, v50 offset:6912
	v_lshlrev_b32_e32 v50, 16, v160
	v_and_b32_e32 v51, 0xffff0000, v160
	v_mul_f32_e32 v55, v58, v50
	v_cvt_pk_bf16_f32 v55, v55, s0
	v_mul_f32_e32 v26, v26, v50
	v_mul_f32_e32 v27, v27, v51
	ds_write_b16 v66, v55 offset:2304
	v_mul_f32_e32 v55, v67, v51
	v_mul_f32_e32 v50, v78, v26
	v_mul_f32_e32 v51, v79, v27
	v_exp_f32_e32 v66, v20
	s_nop 0
	v_mov_b32_dpp v50, v50 quad_perm:[1,0,3,2] row_mask:0xf bank_mask:0xf bound_ctrl:1
	v_mov_b32_dpp v51, v51 quad_perm:[1,0,3,2] row_mask:0xf bank_mask:0xf bound_ctrl:1
	v_fma_f32 v26, v78, v26, v50
	v_fma_f32 v27, v79, v27, v51
	s_nop 1
	v_mov_b32_dpp v50, v26 quad_perm:[2,3,0,1] row_mask:0xf bank_mask:0xf bound_ctrl:1
	v_mov_b32_dpp v51, v27 quad_perm:[2,3,0,1] row_mask:0xf bank_mask:0xf bound_ctrl:1
	v_add_f32_e32 v26, v26, v50
	v_add_f32_e32 v27, v27, v51
	s_nop 1
	v_mov_b32_dpp v50, v26 row_half_mirror row_mask:0xf bank_mask:0xf bound_ctrl:1
	v_mov_b32_dpp v51, v27 row_half_mirror row_mask:0xf bank_mask:0xf bound_ctrl:1
	v_add_f32_e32 v26, v26, v50
	v_add_f32_e32 v27, v27, v51
	s_nop 1
	v_mov_b32_dpp v50, v26 row_ror:8 row_mask:0xf bank_mask:0xf bound_ctrl:1
	v_mov_b32_dpp v51, v27 row_ror:8 row_mask:0xf bank_mask:0xf bound_ctrl:1
	v_add_f32_e32 v58, v26, v50
	v_add_f32_e32 v59, v27, v51
	v_cvt_pk_bf16_f32 v26, v54, s0
	v_add_u32_e32 v27, v60, v120
	ds_write_b16 v27, v26
	v_cvt_pk_bf16_f32 v26, v55, s0
	v_add3_u32 v27, v24, v120, v115
	ds_write_b16 v27, v26 offset:2304
	v_cvt_pk_bf16_f32 v26, v17, s0
	v_exp_f32_e64 v50, -v20
	v_sub_f32_e32 v20, v20, v30
	v_and_b32_e32 v55, 0xffff0000, v159
	v_lshlrev_b32_e32 v54, 16, v159
	ds_write_b16 v27, v26 offset:4608
	v_cvt_pk_bf16_f32 v26, v19, s0
	v_exp_f32_e32 v67, v20
	v_sub_f32_e32 v20, v21, v31
	v_mul_f32_e32 v60, v76, v54
	v_mul_f32_e32 v61, v77, v55
	ds_write_b16 v27, v26 offset:6912
	v_exp_f32_e32 v26, v21
	v_exp_f32_e64 v51, -v21
	v_exp_f32_e32 v68, v20
	v_mul_f32_e32 v20, v60, v60
	v_mul_f32_e32 v21, v61, v61
	s_nop 1
	v_mov_b32_dpp v20, v20 quad_perm:[1,0,3,2] row_mask:0xf bank_mask:0xf bound_ctrl:1
	v_mov_b32_dpp v21, v21 quad_perm:[1,0,3,2] row_mask:0xf bank_mask:0xf bound_ctrl:1
	v_fma_f32 v20, v60, v60, v20
	v_fma_f32 v21, v61, v61, v21
	s_nop 1
	v_mov_b32_dpp v30, v20 quad_perm:[2,3,0,1] row_mask:0xf bank_mask:0xf bound_ctrl:1
	v_mov_b32_dpp v31, v21 quad_perm:[2,3,0,1] row_mask:0xf bank_mask:0xf bound_ctrl:1
	v_add_f32_e32 v20, v20, v30
	v_add_f32_e32 v21, v21, v31
	s_nop 1
	v_mov_b32_dpp v30, v20 row_half_mirror row_mask:0xf bank_mask:0xf bound_ctrl:1
	v_mov_b32_dpp v31, v21 row_half_mirror row_mask:0xf bank_mask:0xf bound_ctrl:1
	v_add_f32_e32 v20, v20, v30
	v_add_f32_e32 v21, v21, v31
	s_nop 1
	v_mov_b32_dpp v30, v20 row_ror:8 row_mask:0xf bank_mask:0xf bound_ctrl:1
	v_mov_b32_dpp v31, v21 row_ror:8 row_mask:0xf bank_mask:0xf bound_ctrl:1
	v_add_f32_e32 v30, v20, v30
	v_add_f32_e32 v31, v21, v31
	v_mul_f32_e64 v20, v67, -v60
	v_cvt_pk_bf16_f32 v20, v20, s0
	ds_write_b16 v27, v20 offset:144
	v_mul_f32_e32 v20, v60, v22
	v_mul_f32_e32 v21, v61, v23
	v_add_f32_e64 v22, v22, -1.0
	v_add_f32_e64 v23, v23, -1.0
	v_mul_f32_e32 v20, v20, v50
	v_mul_f32_e32 v21, v21, v51
	ds_write_b128 v62, v[28:31] offset:17408
	v_cvt_pk_bf16_f32 v28, v20, s0
	v_fma_f32 v22, v74, v22, 1.0
	v_fma_f32 v23, v75, v23, 1.0
	ds_write_b16 v27, v28 offset:4752
	v_mul_f32_e32 v28, v22, v54
	v_mul_f32_e32 v29, v23, v55
	v_and_b32_e32 v31, 0xffff0000, v158
	v_mul_f32_e32 v22, v28, v50
	v_mul_f32_e32 v23, v29, v51
	v_mul_f32_e64 v62, v68, -v61
	v_cvt_pk_bf16_f32 v30, v22, s0
	ds_write_b16 v27, v30 offset:7056
	v_lshlrev_b32_e32 v30, 16, v158
	v_mul_f32_e32 v50, v66, v30
	v_cvt_pk_bf16_f32 v50, v50, s0
	v_mul_f32_e32 v28, v28, v30
	v_mul_f32_e32 v29, v29, v31
	ds_write_b16 v27, v50 offset:2448
	v_mul_f32_e32 v50, v26, v31
	v_mul_f32_e32 v30, v78, v28
	v_mul_f32_e32 v31, v79, v29
	s_nop 1
	v_mov_b32_dpp v30, v30 quad_perm:[1,0,3,2] row_mask:0xf bank_mask:0xf bound_ctrl:1
	v_mov_b32_dpp v31, v31 quad_perm:[1,0,3,2] row_mask:0xf bank_mask:0xf bound_ctrl:1
	v_fma_f32 v28, v78, v28, v30
	v_fma_f32 v29, v79, v29, v31
	s_nop 1
	v_mov_b32_dpp v30, v28 quad_perm:[2,3,0,1] row_mask:0xf bank_mask:0xf bound_ctrl:1
	v_mov_b32_dpp v31, v29 quad_perm:[2,3,0,1] row_mask:0xf bank_mask:0xf bound_ctrl:1
	v_add_f32_e32 v28, v28, v30
	v_add_f32_e32 v29, v29, v31
	s_nop 1
	v_mov_b32_dpp v30, v28 row_half_mirror row_mask:0xf bank_mask:0xf bound_ctrl:1
	v_mov_b32_dpp v31, v29 row_half_mirror row_mask:0xf bank_mask:0xf bound_ctrl:1
	v_add_f32_e32 v28, v28, v30
	v_add_f32_e32 v29, v29, v31
	s_nop 1
	v_mov_b32_dpp v30, v28 row_ror:8 row_mask:0xf bank_mask:0xf bound_ctrl:1
	v_mov_b32_dpp v31, v29 row_ror:8 row_mask:0xf bank_mask:0xf bound_ctrl:1
	v_add_f32_e32 v60, v28, v30
	v_add_f32_e32 v61, v29, v31
	v_cvt_pk_bf16_f32 v28, v62, s0
	ds_write_b16 v27, v28 offset:288
	v_cvt_pk_bf16_f32 v28, v50, s0
	ds_write_b16 v27, v28 offset:2592
	v_cvt_pk_bf16_f32 v28, v21, s0
	ds_write_b16 v27, v28 offset:4896
	v_cvt_pk_bf16_f32 v28, v23, s0
	ds_write_b128 v63, v[58:61] offset:17152
	ds_write_b16 v27, v28 offset:7200
	s_and_saveexec_b64 s[62:63], s[12:13]
	v_lshl_add_u32 v25, v96, 2, v25
	ds_write_b32 v25, v26 offset:16896
	s_or_b64 exec, exec, s[62:63]
	v_cvt_pk_bf16_f32 v16, v16, v17
	v_cvt_pk_bf16_f32 v17, v20, v21
	v_add3_u32 v20, v24, v127, v133
	v_cvt_pk_bf16_f32 v18, v18, v19
	v_cvt_pk_bf16_f32 v19, v22, v23
	ds_write2st64_b64 v20, v[16:17], v[18:19] offset0:18 offset1:23
	ds_write_b64 v20, v[82:83] offset:14336

; #define MFMA4(a, b, c) __builtin_amdgcn_mfma_f32_16x16x16bf16_1k(a, b, c, 0, 0, 0)
; __device__ __forceinline__ s4 pack4v(f32x4 v) { return pack4(v[0], v[1], v[2], v[3]); }
; __device__ __forceinline__ void scan_pc(const Params& p, int j, const u16* R, const u16* K, const u16* V, u16* Y, u16* YB) {
;     ...
;     auto stage_c = [&](int c) {
;       const u16* IMG = shm + (c % 3) * IMG_ELEMS;
;       const u16* MM = shm + 4 * IMG_ELEMS + (c & 1) * MM_ELEMS;
;       s4 vb = *reinterpret_cast<const s4*>(IMG + IMG_VT + (w4 * 16 + fr) * XK_LD + fq * 4);
;       f32x4 z4 = {0.f, 0.f, 0.f, 0.f};
;       const float* PL = reinterpret_cast<const float*>(IMG + IMG_PL);
;       float4 iv = *reinterpret_cast<const float4*>(PL + 192 + fq * 4);
;       f32x4 rhs = z4;
;       f32x4 y = MFMA4(*reinterpret_cast<const s4*>(MM + (3 * 16 + fr) * XK_LD + fq * 4), vb, z4);
;       _Pragma("unroll") for (int kb = 0; kb < 4; ++kb) {
;         rhs = MFMA4(*reinterpret_cast<const s4*>(IMG + (0 * 16 + fr) * XT_LD + kb * 16 + fq * 4), Zb[kb], rhs);
;         y = MFMA4(*reinterpret_cast<const s4*>(IMG + (1 * 16 + fr) * XT_LD + kb * 16 + fq * 4), Zb[kb], y);
;       }
;       rhs[0] *= iv.x; rhs[1] *= iv.y; rhs[2] *= iv.z; rhs[3] *= iv.w;
;       rhs = MFMA4(*reinterpret_cast<const s4*>(MM + (1 * 16 + fr) * XK_LD + fq * 4), vb, rhs);
;       f32x4 u = MFMA4(*reinterpret_cast<const s4*>(MM + (0 * 16 + fr) * XK_LD + fq * 4), pack4v(rhs), z4);
;       y = MFMA4(*reinterpret_cast<const s4*>(MM + (2 * 16 + fr) * XK_LD + fq * 4), pack4v(u), y);
;       s4 ub = pack4(u[0] * iv.x, u[1] * iv.y, u[2] * iv.z, u[3] * iv.w);
;       _Pragma("unroll") for (int kb = 0; kb < 4; ++kb) {
;         Z[kb] = MFMA4(*reinterpret_cast<const s4*>(IMG + IMG_XK + (0 * 64 + kb * 16 + fr) * XK_LD + fq * 4), ub, Z[kb]);
;         Z[kb] = MFMA4(*reinterpret_cast<const s4*>(IMG + IMG_XK + (1 * 64 + kb * 16 + fr) * XK_LD + fq * 4), vb, Z[kb]);
;         float4 pl = *reinterpret_cast<const float4*>(PL + kb * 16 + fq * 4);
;         Z[kb][0] *= pl.x; Z[kb][1] *= pl.y; Z[kb][2] *= pl.z; Z[kb][3] *= pl.w;
;         Zb[kb] = pack4v(Z[kb]);
;       }
.LBB0_2745:
	s_or_b64 exec, exec, s[26:27]
	s_waitcnt lgkmcnt(0)
	s_barrier
	s_and_saveexec_b64 s[26:27], s[10:11]
	s_xor_b64 s[26:27], exec, s[26:27]
	s_cbranch_execz .LBB0_2764
	v_add_u32_e32 v50, s75, v90
	v_mad_u32_u24 v91, v50, s80, 0
	v_add3_u32 v51, v91, v146, v179
	ds_read2_b64 v[66:69], v147 offset0:160 offset1:240
	ds_read2_b64 v[92:95], v51 offset1:4
	v_add3_u32 v50, v91, v127, v179
	ds_read_b64 v[180:181], v50 offset:14336
	v_lshl_add_u32 v50, v97, 2, v91
	ds_read_b128 v[58:61], v50 offset:17664
	v_add_u32_e32 v50, 0x800, v51
	ds_read2_b64 v[198:201], v50 offset0:32 offset1:36
	s_waitcnt lgkmcnt(2)
	v_mfma_f32_16x16x16_bf16 v[68:71], v[68:69], v[180:181], 0
	v_add3_u32 v193, v91, v144, v133
	v_add_u32_e32 v202, 0x2c00, v193
	v_add_u32_e32 v91, v91, v112
	v_mfma_f32_16x16x16_bf16 v[194:197], v[92:93], v[64:65], 0
	v_readlane_b32 s80, v247, 14
	v_readlane_b32 s81, v247, 15
	v_readlane_b32 s82, v247, 16
	s_waitcnt lgkmcnt(0)
	v_mfma_f32_16x16x16_bf16 v[62:65], v[198:199], v[64:65], v[68:71]
	v_readlane_b32 s83, v247, 17
	s_mov_b32 s81, s80
	s_mov_b32 s82, s80
	v_mfma_f32_16x16x16_bf16 v[68:71], v[94:95], v[56:57], v[194:197]
	ds_read2_b64 v[92:95], v51 offset0:8 offset1:12
	v_add_u32_e32 v51, 0x2000, v193
	s_mov_b32 s83, s80
	s_waitcnt lgkmcnt(0)
	v_mfma_f32_16x16x16_bf16 v[68:71], v[92:93], v[52:53], v[68:71]
	ds_read2_b64 v[194:197], v147 offset1:80
	v_writelane_b32 v247, s80, 14
	v_mfma_f32_16x16x16_bf16 v[68:71], v[94:95], v[48:49], v[68:71]
	ds_read2_b64 v[92:95], v50 offset0:40 offset1:44
	v_writelane_b32 v247, s81, 15
	v_writelane_b32 v247, s82, 16
	v_mfma_f32_16x16x16_bf16 v[198:201], v[200:201], v[56:57], v[62:65]
	v_writelane_b32 v247, s83, 17
	s_nop 2
	v_mul_f32_e32 v56, v60, v70
	v_mul_f32_e32 v57, v61, v71
	v_mul_f32_e32 v54, v58, v68
	v_mul_f32_e32 v55, v59, v69
	ds_read2_b64 v[62:65], v51 offset0:128 offset1:208
	ds_read2_b64 v[68:71], v202 offset0:64 offset1:144
	s_waitcnt lgkmcnt(3)
	v_mfma_f32_16x16x16_bf16 v[54:57], v[196:197], v[180:181], v[54:57]
	s_movk_i32 s80, 0x4540
	s_nop 6
	v_cvt_pk_bf16_f32 v50, v54, v55
	v_cvt_pk_bf16_f32 v51, v56, v57
	s_nop 1
	v_mfma_f32_16x16x16_bf16 v[54:57], v[194:195], v[50:51], 0
	s_nop 7
	v_mul_f32_e32 v50, v58, v54
	v_mul_f32_e32 v51, v59, v55
	v_mul_f32_e32 v58, v60, v56
	v_mul_f32_e32 v59, v61, v57
	v_cvt_pk_bf16_f32 v202, v50, v51
	s_waitcnt lgkmcnt(2)
	v_mfma_f32_16x16x16_bf16 v[50:53], v[92:93], v[52:53], v[198:201]
	v_cvt_pk_bf16_f32 v203, v58, v59
	v_cvt_pk_bf16_f32 v204, v54, v55
	v_add_u32_e32 v54, 0x2800, v193
	s_waitcnt lgkmcnt(1)
	v_mfma_f32_16x16x16_bf16 v[40:43], v[62:63], v[202:203], v[40:43]
	v_cvt_pk_bf16_f32 v205, v56, v57
	ds_read_b128 v[60:63], v91 offset:16896
	ds_read_b128 v[56:59], v91 offset:16960
	ds_read2_b64 v[194:197], v54 offset0:32 offset1:112
	v_mfma_f32_16x16x16_bf16 v[92:95], v[94:95], v[48:49], v[50:53]
	v_add_u32_e32 v54, 0x3000, v193
	ds_read2_b64 v[198:201], v54 offset0:96 offset1:176
	s_nop 0
	ds_read_b128 v[52:55], v91 offset:17024
	ds_read_b128 v[48:51], v91 offset:17088
	v_add_u32_e32 v91, s74, v174
	s_waitcnt lgkmcnt(6)
	v_mfma_f32_16x16x16_bf16 v[40:43], v[68:69], v[180:181], v[40:43]
	v_mfma_f32_16x16x16_bf16 v[66:69], v[66:67], v[204:205], v[92:95]
	v_mfma_f32_16x16x16_bf16 v[44:47], v[64:65], v[202:203], v[44:47]
	s_andn2_b64 vcc, exec, s[20:21]
	s_cbranch_vccnz .Lyold_done_b
	s_waitcnt vmcnt(0)
	v_lshlrev_b32_e32 v87, 16, v230
	v_lshlrev_b32_e32 v88, 16, v231
	v_lshlrev_b32_e32 v86, 16, v232
	v_lshlrev_b32_e32 v89, 16, v233

; __device__ __forceinline__ void scan_pc(const Params& p, int j, const u16* R, const u16* K, const u16* V, u16* Y, u16* YB) {
;     ...
;     auto load_raw = [&](int c, Raw& q_) {
;       unsigned offA = (unsigned)(offA0 + c * dA);
;       _Pragma("unroll") for (int ks = 0; ks < 2; ++ks) { q_.rw[ks] = ldo<bf16x8>(wmid, offA + ks * 64); q_.ra[ks] = ldo<bf16x8>(amid, offA + ks * 64); }
;       _Pragma("unroll") for (int jj = 0; jj < 4; ++jj) {
;         unsigned off = (unsigned)(offK0[jj] + c * dK);
;         q_.rk[jj] = ldo<u16>(K, off); q_.rr[jj] = ldo<u16>(R, off); q_.rv[jj] = ldo<u16>(V, off);
;       }
;     };
;     auto load_yold = [&](int c) {
;       _Pragma("unroll") for (int jj = 0; jj < 4; ++jj) yo[jj] = b2f(ldo<u16>(Yw, (unsigned)(offK0[jj] + c * dK)));
;     };
;     auto stage_a = [&](int c, const Raw& q_) {
;       u16* IMG = shm + (c % 3) * IMG_ELEMS;
;       f32x4 cw = {0.f, 0.f, 0.f, 0.f}, ca = {0.f, 0.f, 0.f, 0.f};
;       _Pragma("unroll") for (int ks = 0; ks < 2; ++ks) { cw = MFMA16(q_.rw[ks], LB[ks * 64], cw); ca = MFMA16(q_.ra[ks], LB[(2 + ks) * 64], ca); }
;       float kv[4], kk[4], ic[4], lw[4];
;       _Pragma("unroll") for (int jj = 0; jj < 4; ++jj) {
;         kv[jj] = b2f(q_.rk[jj]);
;         kk[jj] = kv[jj] * kkme;
;         float ss = row_sum(kk[jj] * kk[jj]);
;         reinterpret_cast<float*>(IMG + IMG_PL)[128 + w4 * 16 + fq * 4 + jj] = ss;
;         lw[jj] = -0.8750360036f * sigmoidf_(w0c + cw[jj]);
;         ic[jj] = sigmoidf_(a0c + ca[jj]);
;       }
;       s4 lhi = pack4(lw[0], lw[1], lw[2], lw[3]);
;       s4 llo = pack4(lw[0] - b2f((u16)lhi[0]), lw[1] - b2f((u16)lhi[1]), lw[2] - b2f((u16)lhi[2]), lw[3] - b2f((u16)lhi[3]));
;       f32x4 cum = {0.f, 0.f, 0.f, 0.f};
;       cum = MFMA4(ltri, lhi, cum);
;       cum = MFMA4(ltri, llo, cum);
;       float bt[4], kt[4], ep3 = 0.f;
;     ...
;       _Pragma("unroll") for (int kb = 0; kb < 4; ++kb) {
;         Z[kb] = MFMA4(*reinterpret_cast<const s4*>(IMG + IMG_XK + (0 * 64 + kb * 16 + fr) * XK_LD + fq * 4), ub, Z[kb]);
;         Z[kb] = MFMA4(*reinterpret_cast<const s4*>(IMG + IMG_XK + (1 * 64 + kb * 16 + fr) * XK_LD + fq * 4), vb, Z[kb]);
;         float4 pl = *reinterpret_cast<const float4*>(PL + kb * 16 + fq * 4);
;         Z[kb][0] *= pl.x; Z[kb][1] *= pl.y; Z[kb][2] *= pl.z; Z[kb][3] *= pl.w;
;         Zb[kb] = pack4v(Z[kb]);
;       }
.LBB0_2763:
	s_or_b64 exec, exec, s[62:63]
	v_mul_f32_e32 v40, v40, v60
	v_mul_f32_e32 v41, v41, v61
	v_mul_f32_e32 v42, v42, v62
	v_mul_f32_e32 v43, v43, v63
	v_mul_f32_e32 v44, v44, v56
	v_mul_f32_e32 v45, v45, v57
	v_mul_f32_e32 v46, v46, v58
	v_mul_f32_e32 v47, v47, v59
	s_waitcnt lgkmcnt(1)
	v_mul_f32_e32 v32, v32, v52
	v_mul_f32_e32 v33, v33, v53
	v_mul_f32_e32 v34, v34, v54
	v_mul_f32_e32 v35, v35, v55
	s_waitcnt lgkmcnt(0)
	v_mul_f32_e32 v36, v36, v48
	v_mul_f32_e32 v37, v37, v49
	v_mul_f32_e32 v38, v38, v50
	v_mul_f32_e32 v39, v39, v51
	v_cvt_pk_bf16_f32 v64, v40, v41
	v_cvt_pk_bf16_f32 v65, v42, v43
	v_cvt_pk_bf16_f32 v56, v44, v45
	v_cvt_pk_bf16_f32 v57, v46, v47
	v_cvt_pk_bf16_f32 v52, v32, v33
	v_cvt_pk_bf16_f32 v53, v34, v35
	v_cvt_pk_bf16_f32 v48, v36, v37
	v_cvt_pk_bf16_f32 v49, v38, v39
.LBB0_2764:
	s_andn2_saveexec_b64 s[26:27], s[26:27]
	s_cbranch_execz .LBB0_2719
	s_waitcnt vmcnt(16)
	v_lshl_or_b32 v165, v219, 16, v218
	v_lshl_or_b32 v163, v221, 16, v220
	v_lshl_or_b32 v164, v223, 16, v222
	v_lshl_or_b32 v162, v225, 16, v224
	v_lshl_or_b32 v84, v227, 16, v226
	v_lshl_or_b32 v85, v229, 16, v228
	v_add_u32_e32 v50, 5, v90
	v_min_i32_e32 v50, s29, v50
	v_mul_lo_u32 v50, v50, s8
	v_add_u32_e32 v51, v50, v154
	v_add_u32_e32 v54, v50, v155
	v_add_u32_e32 v55, v50, v156
	v_add_u32_e32 v50, v50, v157
	global_load_ushort v220, v55, s[58:59]
	global_load_ushort v221, v50, s[58:59]
	global_load_ushort v218, v51, s[58:59]
	global_load_ushort v222, v51, s[54:55]
	global_load_ushort v219, v54, s[58:59]
	global_load_ushort v223, v54, s[54:55]
	global_load_ushort v224, v55, s[54:55]
	global_load_ushort v228, v55, s[4:5]
	global_load_ushort v227, v54, s[4:5]
	global_load_ushort v226, v51, s[4:5]
	global_load_ushort v225, v50, s[54:55]
	global_load_ushort v229, v50, s[4:5]
	v_add_u32_e32 v50, 3, v90
	v_cmp_gt_u32_e32 vcc, s2, v50
	s_and_saveexec_b64 s[30:31], vcc
	s_cbranch_execz .LBB0_2718
	ds_read_b128 v[58:61], v111
	ds_read_b128 v[234:237], v111 offset:2048
	ds_read_b128 v[238:241], v111 offset:1024
	ds_read_b128 v[242:245], v111 offset:3072
	s_mul_hi_u32 s62, s65, 0xaaaaaaab
	s_lshr_b32 s62, s62, 1
	s_mul_i32 s62, s62, 3
	v_subrev_u32_e32 v50, s62, v90
	s_waitcnt lgkmcnt(3)
	v_mfma_f32_16x16x32_bf16 v[8:11], v[8:11], v[58:61], 0
	s_mov_b32 s62, 0xbf60025c
	v_add_u32_e32 v50, 3, v50
	s_waitcnt lgkmcnt(2)
	v_mfma_f32_16x16x32_bf16 v[12:15], v[12:15], v[234:237], 0
	s_waitcnt lgkmcnt(1)
	v_mfma_f32_16x16x32_bf16 v[0:3], v[0:3], v[238:241], v[8:11]
	s_waitcnt lgkmcnt(0)
	v_mfma_f32_16x16x32_bf16 v[4:7], v[4:7], v[242:245], v[12:15]
	s_nop 5
	v_add_f32_e32 v0, v152, v0
	v_add_f32_e32 v1, v152, v1
	v_mul_f32_e32 v0, 0xbfb8aa3b, v0
	s_nop 2
	v_add_f32_e32 v4, v153, v4
	v_mul_f32_e32 v4, 0xbfb8aa3b, v4
	v_exp_f32_e32 v4, v4
	v_mul_f32_e32 v1, 0xbfb8aa3b, v1
	v_add_f32_e32 v2, v152, v2
	v_add_f32_e32 v3, v152, v3
	v_add_f32_e32 v4, 1.0, v4
	v_rcp_f32_e32 v10, v4
	v_add_f32_e32 v4, v153, v5
	v_mul_f32_e32 v4, 0xbfb8aa3b, v4
	v_exp_f32_e32 v4, v4
	v_exp_f32_e32 v0, v0
	v_exp_f32_e32 v1, v1
	v_mul_f32_e32 v2, 0xbfb8aa3b, v2
	v_add_f32_e32 v4, 1.0, v4
	v_rcp_f32_e32 v11, v4
	v_add_f32_e32 v4, v153, v6
	v_mul_f32_e32 v4, 0xbfb8aa3b, v4
	v_exp_f32_e32 v4, v4
	v_mul_f32_e32 v3, 0xbfb8aa3b, v3
	v_exp_f32_e32 v2, v2
	v_exp_f32_e32 v3, v3
	v_add_f32_e32 v4, 1.0, v4
	v_rcp_f32_e32 v6, v4
	v_add_f32_e32 v4, v153, v7
	v_add_f32_e32 v0, 1.0, v0
	v_add_f32_e32 v1, 1.0, v1
	v_mul_f32_e32 v4, 0xbfb8aa3b, v4
	v_rcp_f32_e32 v0, v0
	v_rcp_f32_e32 v1, v1
	v_add_f32_e32 v2, 1.0, v2
	v_add_f32_e32 v3, 1.0, v3
	v_exp_f32_e32 v4, v4
	v_rcp_f32_e32 v2, v2
	v_rcp_f32_e32 v3, v3
	v_mul_f32_e64 v12, v0, s62
	v_mul_f32_e64 v13, v1, s62
	v_add_f32_e32 v4, 1.0, v4
	v_rcp_f32_e32 v7, v4
	v_mul_f32_e64 v14, v2, s62
	v_mul_f32_e64 v15, v3, s62
	v_cvt_pk_bf16_f32 v4, v12, v13
	v_mad_u32_u24 v8, v50, s80, 0
	v_cvt_pk_bf16_f32 v5, v14, v15
	v_and_b32_e32 v51, 0xffff0000, v4
	v_lshlrev_b32_e32 v50, 16, v4
	v_fma_f32 v0, v0, s62, -v50
	v_fma_f32 v1, v1, s62, -v51
	v_and_b32_e32 v51, 0xffff0000, v5
	v_lshlrev_b32_e32 v50, 16, v5
	v_fma_f32 v2, v2, s62, -v50
	v_fma_f32 v3, v3, s62, -v51
	v_cvt_pk_bf16_f32 v50, v0, v1
	v_cvt_pk_bf16_f32 v51, v2, v3
	v_mfma_f32_16x16x16_bf16 v[0:3], v[72:73], v[4:5], 0
	v_add_u32_e32 v60, v8, v115
	v_add_u32_e32 v61, v60, v117
	v_add3_u32 v66, v8, v117, v115
	v_mfma_f32_16x16x16_bf16 v[2:5], v[72:73], v[50:51], v[0:3]
	v_add_u32_e32 v9, v8, v113
	v_add_u32_e32 v62, v9, v112
	v_lshl_add_u32 v63, v97, 2, v9
	s_nop 4
	v_sub_f32_e32 v0, v2, v12
	v_exp_f32_e32 v58, v2
	v_exp_f32_e64 v50, -v2
	v_exp_f32_e32 v59, v0
	v_exp_f32_e32 v67, v3
	v_exp_f32_e64 v51, -v3
	v_sub_f32_e32 v0, v3, v13
	v_and_b32_e32 v3, 0xffff0000, v165
	v_lshlrev_b32_e32 v2, 16, v165
	v_mul_f32_e32 v54, v76, v2
	v_mul_f32_e32 v55, v77, v3
	v_exp_f32_e32 v68, v0
	v_mul_f32_e32 v0, v54, v54
	v_mul_f32_e32 v1, v55, v55
	s_nop 1
	v_mov_b32_dpp v0, v0 quad_perm:[1,0,3,2] row_mask:0xf bank_mask:0xf bound_ctrl:1
	v_mov_b32_dpp v1, v1 quad_perm:[1,0,3,2] row_mask:0xf bank_mask:0xf bound_ctrl:1
	v_fma_f32 v0, v54, v54, v0
	v_fma_f32 v1, v55, v55, v1
	s_nop 1
	v_mov_b32_dpp v12, v0 quad_perm:[2,3,0,1] row_mask:0xf bank_mask:0xf bound_ctrl:1
	v_mov_b32_dpp v13, v1 quad_perm:[2,3,0,1] row_mask:0xf bank_mask:0xf bound_ctrl:1
	v_add_f32_e32 v0, v0, v12
	v_add_f32_e32 v1, v1, v13
	s_nop 1
	v_mov_b32_dpp v12, v0 row_half_mirror row_mask:0xf bank_mask:0xf bound_ctrl:1
	v_mov_b32_dpp v13, v1 row_half_mirror row_mask:0xf bank_mask:0xf bound_ctrl:1
	v_add_f32_e32 v0, v0, v12
	v_add_f32_e32 v1, v1, v13
	s_nop 1
	v_mov_b32_dpp v12, v0 row_ror:8 row_mask:0xf bank_mask:0xf bound_ctrl:1
; __device__ __forceinline__ float b2f(u16 b) { return __uint_as_float(((unsigned)b) << 16); }
; __device__ __forceinline__ void scan_pc(const Params& p, int j, const u16* R, const u16* K, const u16* V, u16* Y, u16* YB) {
;     ...
;       _Pragma("unroll") for (int jj = 0; jj < 4; ++jj) {
;         float ep = __builtin_amdgcn_exp2f(cum[jj]), em = __builtin_amdgcn_exp2f(-cum[jj]), ex = __builtin_amdgcn_exp2f(cum[jj] - lw[jj]);
;         float at = -kk[jj] * ex;
;         float rraw = b2f(q_.rr[jj]);
;         float rt = rraw * ep;
;         float kd = kv[jj] * (1.f + (ic[jj] - 1.f) * kac);
;         bt[jj] = kk[jj] * ic[jj] * em;
;         kt[jj] = kd * em;
;         int t = fq * 4 + jj, kc = w4 * 16 + fr;
;         float bsum = row_sum(rraw * kd * rkc);
;         reinterpret_cast<float*>(IMG + IMG_PL)[64 + w4 * 16 + t] = bsum;
;         IMG[(0 * 16 + t) * XT_LD + kc] = f2b(at);
;         IMG[(1 * 16 + t) * XT_LD + kc] = f2b(rt);
;         IMG[(2 * 16 + t) * XT_LD + kc] = f2b(bt[jj]);
;         IMG[(3 * 16 + t) * XT_LD + kc] = f2b(kt[jj]);
;         if (jj == 3) ep3 = ep;
;       }
;       if (fq == 3) reinterpret_cast<float*>(IMG + IMG_PL)[w4 * 16 + fr] = ep3;
;       *reinterpret_cast<s4*>(IMG + IMG_XK + (0 * 64 + w4 * 16 + fr) * XK_LD + fq * 4) = pack4(bt[0], bt[1], bt[2], bt[3]);
;       *reinterpret_cast<s4*>(IMG + IMG_XK + (1 * 64 + w4 * 16 + fr) * XK_LD + fq * 4) = pack4(kt[0], kt[1], kt[2], kt[3]);
;       s4 vp; _Pragma("unroll") for (int jj = 0; jj < 4; ++jj) vp[jj] = (short)q_.rv[jj];
;       *reinterpret_cast<s4*>(IMG + IMG_VT + (w4 * 16 + fr) * XK_LD + fq * 4) = vp;
	v_mov_b32_dpp v13, v1 row_ror:8 row_mask:0xf bank_mask:0xf bound_ctrl:1
	v_add_f32_e32 v12, v0, v12
	v_add_f32_e32 v13, v1, v13
	v_mul_f32_e64 v0, v59, -v54
	v_cvt_pk_bf16_f32 v0, v0, s0
	ds_write_b16 v61, v0
	v_mul_f32_e32 v0, v54, v10
	v_mul_f32_e32 v1, v55, v11
	v_add_f32_e64 v10, v10, -1.0
	v_add_f32_e64 v11, v11, -1.0
	v_mul_f32_e32 v0, v0, v50
	v_mul_f32_e32 v1, v1, v51
	v_fma_f32 v10, v74, v10, 1.0
	v_fma_f32 v11, v75, v11, 1.0
	v_cvt_pk_bf16_f32 v54, v0, s0
	v_mul_f32_e32 v10, v10, v2
	v_mul_f32_e32 v11, v11, v3
	ds_write_b16 v66, v54 offset:4608
	v_mul_f32_e32 v2, v10, v50
	v_mul_f32_e32 v3, v11, v51
	v_mul_f32_e64 v54, v68, -v55
	v_cvt_pk_bf16_f32 v50, v2, s0
	ds_write_b16 v66, v50 offset:6912
	v_lshlrev_b32_e32 v50, 16, v164
	v_and_b32_e32 v51, 0xffff0000, v164
	v_mul_f32_e32 v55, v58, v50
	v_cvt_pk_bf16_f32 v55, v55, s0
	v_mul_f32_e32 v10, v10, v50
	v_mul_f32_e32 v11, v11, v51
	ds_write_b16 v66, v55 offset:2304
	v_mul_f32_e32 v55, v67, v51
	v_mul_f32_e32 v50, v78, v10
	v_mul_f32_e32 v51, v79, v11
	v_exp_f32_e32 v66, v4
	s_nop 0
	v_mov_b32_dpp v50, v50 quad_perm:[1,0,3,2] row_mask:0xf bank_mask:0xf bound_ctrl:1
	v_mov_b32_dpp v51, v51 quad_perm:[1,0,3,2] row_mask:0xf bank_mask:0xf bound_ctrl:1
	v_fma_f32 v10, v78, v10, v50
	v_fma_f32 v11, v79, v11, v51
	s_nop 1
	v_mov_b32_dpp v50, v10 quad_perm:[2,3,0,1] row_mask:0xf bank_mask:0xf bound_ctrl:1
	v_mov_b32_dpp v51, v11 quad_perm:[2,3,0,1] row_mask:0xf bank_mask:0xf bound_ctrl:1
	v_add_f32_e32 v10, v10, v50
	v_add_f32_e32 v11, v11, v51
	s_nop 1
	v_mov_b32_dpp v50, v10 row_half_mirror row_mask:0xf bank_mask:0xf bound_ctrl:1
	v_mov_b32_dpp v51, v11 row_half_mirror row_mask:0xf bank_mask:0xf bound_ctrl:1
	v_add_f32_e32 v10, v10, v50
	v_add_f32_e32 v11, v11, v51
	s_nop 1
	v_mov_b32_dpp v50, v10 row_ror:8 row_mask:0xf bank_mask:0xf bound_ctrl:1
	v_mov_b32_dpp v51, v11 row_ror:8 row_mask:0xf bank_mask:0xf bound_ctrl:1
	v_add_f32_e32 v58, v10, v50
	v_add_f32_e32 v59, v11, v51
	v_cvt_pk_bf16_f32 v10, v54, s0
	v_add_u32_e32 v11, v60, v120
	ds_write_b16 v11, v10
	v_cvt_pk_bf16_f32 v10, v55, s0
	v_add3_u32 v11, v8, v120, v115
	ds_write_b16 v11, v10 offset:2304
	v_cvt_pk_bf16_f32 v10, v1, s0
	v_exp_f32_e64 v50, -v4
	v_sub_f32_e32 v4, v4, v14
	v_and_b32_e32 v55, 0xffff0000, v163
	v_lshlrev_b32_e32 v54, 16, v163
	ds_write_b16 v11, v10 offset:4608
	v_cvt_pk_bf16_f32 v10, v3, s0
	v_exp_f32_e32 v67, v4
	v_sub_f32_e32 v4, v5, v15
	v_mul_f32_e32 v60, v76, v54
	v_mul_f32_e32 v61, v77, v55
	ds_write_b16 v11, v10 offset:6912
	v_exp_f32_e32 v10, v5
	v_exp_f32_e64 v51, -v5
	v_exp_f32_e32 v68, v4
	v_mul_f32_e32 v4, v60, v60
	v_mul_f32_e32 v5, v61, v61
	s_nop 1
	v_mov_b32_dpp v4, v4 quad_perm:[1,0,3,2] row_mask:0xf bank_mask:0xf bound_ctrl:1
	v_mov_b32_dpp v5, v5 quad_perm:[1,0,3,2] row_mask:0xf bank_mask:0xf bound_ctrl:1
	v_fma_f32 v4, v60, v60, v4
	v_fma_f32 v5, v61, v61, v5
	s_nop 1
	v_mov_b32_dpp v14, v4 quad_perm:[2,3,0,1] row_mask:0xf bank_mask:0xf bound_ctrl:1
	v_mov_b32_dpp v15, v5 quad_perm:[2,3,0,1] row_mask:0xf bank_mask:0xf bound_ctrl:1
	v_add_f32_e32 v4, v4, v14
	v_add_f32_e32 v5, v5, v15
	s_nop 1
	v_mov_b32_dpp v14, v4 row_half_mirror row_mask:0xf bank_mask:0xf bound_ctrl:1
	v_mov_b32_dpp v15, v5 row_half_mirror row_mask:0xf bank_mask:0xf bound_ctrl:1
	v_add_f32_e32 v4, v4, v14
	v_add_f32_e32 v5, v5, v15
	s_nop 1
	v_mov_b32_dpp v14, v4 row_ror:8 row_mask:0xf bank_mask:0xf bound_ctrl:1
	v_mov_b32_dpp v15, v5 row_ror:8 row_mask:0xf bank_mask:0xf bound_ctrl:1
	v_add_f32_e32 v14, v4, v14
	v_add_f32_e32 v15, v5, v15
	v_mul_f32_e64 v4, v67, -v60
	v_cvt_pk_bf16_f32 v4, v4, s0
	ds_write_b16 v11, v4 offset:144
	v_mul_f32_e32 v4, v60, v6
	v_mul_f32_e32 v5, v61, v7
	v_add_f32_e64 v6, v6, -1.0
	v_add_f32_e64 v7, v7, -1.0
	v_mul_f32_e32 v4, v4, v50
	v_mul_f32_e32 v5, v5, v51
	ds_write_b128 v62, v[12:15] offset:17408
	v_cvt_pk_bf16_f32 v12, v4, s0
	v_fma_f32 v6, v74, v6, 1.0
	v_fma_f32 v7, v75, v7, 1.0
	ds_write_b16 v11, v12 offset:4752
	v_mul_f32_e32 v12, v6, v54
	v_mul_f32_e32 v13, v7, v55
	v_and_b32_e32 v15, 0xffff0000, v162
	v_mul_f32_e32 v6, v12, v50
	v_mul_f32_e32 v7, v13, v51
	v_mul_f32_e64 v62, v68, -v61
	v_cvt_pk_bf16_f32 v14, v6, s0
	ds_write_b16 v11, v14 offset:7056
	v_lshlrev_b32_e32 v14, 16, v162
	v_mul_f32_e32 v50, v66, v14
	v_cvt_pk_bf16_f32 v50, v50, s0
	v_mul_f32_e32 v12, v12, v14
	v_mul_f32_e32 v13, v13, v15
	ds_write_b16 v11, v50 offset:2448
	v_mul_f32_e32 v50, v10, v15
	v_mul_f32_e32 v14, v78, v12
	v_mul_f32_e32 v15, v79, v13
	s_nop 1
	v_mov_b32_dpp v14, v14 quad_perm:[1,0,3,2] row_mask:0xf bank_mask:0xf bound_ctrl:1
	v_mov_b32_dpp v15, v15 quad_perm:[1,0,3,2] row_mask:0xf bank_mask:0xf bound_ctrl:1
	v_fma_f32 v12, v78, v12, v14
	v_fma_f32 v13, v79, v13, v15
	s_nop 1
	v_mov_b32_dpp v14, v12 quad_perm:[2,3,0,1] row_mask:0xf bank_mask:0xf bound_ctrl:1
	v_mov_b32_dpp v15, v13 quad_perm:[2,3,0,1] row_mask:0xf bank_mask:0xf bound_ctrl:1
	v_add_f32_e32 v12, v12, v14
	v_add_f32_e32 v13, v13, v15
	s_nop 1
	v_mov_b32_dpp v14, v12 row_half_mirror row_mask:0xf bank_mask:0xf bound_ctrl:1
	v_mov_b32_dpp v15, v13 row_half_mirror row_mask:0xf bank_mask:0xf bound_ctrl:1
	v_add_f32_e32 v12, v12, v14
	v_add_f32_e32 v13, v13, v15
	s_nop 1
	v_mov_b32_dpp v14, v12 row_ror:8 row_mask:0xf bank_mask:0xf bound_ctrl:1
	v_mov_b32_dpp v15, v13 row_ror:8 row_mask:0xf bank_mask:0xf bound_ctrl:1
	v_add_f32_e32 v60, v12, v14
	v_add_f32_e32 v61, v13, v15
	v_cvt_pk_bf16_f32 v12, v62, s0
	ds_write_b16 v11, v12 offset:288
	v_cvt_pk_bf16_f32 v12, v50, s0
	ds_write_b16 v11, v12 offset:2592
	v_cvt_pk_bf16_f32 v12, v5, s0
	ds_write_b16 v11, v12 offset:4896
	v_cvt_pk_bf16_f32 v12, v7, s0
	ds_write_b128 v63, v[58:61] offset:17152
	ds_write_b16 v11, v12 offset:7200
	s_and_saveexec_b64 s[62:63], s[12:13]
	s_cbranch_execz .LBB0_2717
	v_lshl_add_u32 v9, v96, 2, v9
	ds_write_b32 v9, v10 offset:16896
	s_branch .LBB0_2717
